# S5 prompt item: WT fragment loads issued with the U-tile loads (one round trip less); sample-item loop header wait moved to the entry path
# baseline (speedup 1.0000x reference)
; #define LAS __attribute__((address_space(3)))
; #define S5_LAUNDER() int tid_ = tid0, lane_ = lane0; asm volatile("" : "+v"(tid_), "+v"(lane_)); const int tid = tid_, lane = lane_, fr = lane & 15, fq = lane >> 4; (void)tid; (void)fr; (void)fq
; __device__ __forceinline__ void s5_prompt_item_mfma(LAS unsigned char* lds, int tid0, int lane0, int wave, int n, int g, const bf16* USg, const bf16* FTg, const bf16* WTg, const bf16* GTg, ...
;     ...
;     { S5_LAUNDER(); const bf16* usrc = USg + ((size_t)g * M + (size_t)n * SEQ) * 16;
; #pragma unroll
;       for (int it = 0; it < 8; ++it) { const int q = tid + 512 * it, token = q >> 1, half = q & 1; const v4u v = *(const v4u*)(usrc + (size_t)token * 16 + 8 * half);
;           *(LAS v4u*)(lds + U_OFF + (token >> 5) * 1056 + (token & 31) * 32 + 16 * half) = v; } }
;     bf16x8 wa[16];
;     { S5_LAUNDER();
; #pragma unroll
;     for (int ks = 0; ks < 16; ++ks) wa[ks] = *(const bf16x8*)(WTg + ((size_t)(wave * 16 + ks) * 64 + lane) * 8);
;     }
.LBB0_848:
	s_and_b32 s65, s64, 31
	s_ashr_i32 s10, s64, 5
	s_lshl_b32 s8, s65, 15
	v_readlane_b32 s9, v254, 54
	s_add_u32 vcc_lo, s9, s8
	v_readlane_b32 s8, v254, 56
	s_addc_u32 vcc_hi, s8, 0
	s_lshl_b32 s8, s65, 17
	v_readlane_b32 s9, v253, 45
	s_add_u32 s72, s9, s8
	v_readlane_b32 s9, v253, 49
	s_addc_u32 s73, s9, 0
	v_readlane_b32 s9, v253, 51
	s_add_u32 s54, s9, s8
	v_readlane_b32 s8, v253, 55
	s_addc_u32 s55, s8, 0
	s_ashr_i32 s11, s10, 31
	s_mul_i32 s12, s65, 0x4200
	s_lshl_b64 s[8:9], s[10:11], 11
	s_add_u32 s12, s8, s12
	s_addc_u32 s13, s9, 0
	s_lshl_b64 s[12:13], s[12:13], 5
	s_mov_b32 s37, s74
	s_add_u32 s74, s74, s12
	s_mov_b32 s84, s75
	s_addc_u32 s75, s75, s13
	v_readlane_b32 s12, v252, 4
	v_readlane_b32 s13, v252, 5
	v_readlane_b32 s14, v252, 6
	v_readlane_b32 s15, v252, 7
	s_mov_b64 s[14:15], s[12:13]
	v_mov_b32_e32 v52, v192
	v_mov_b32_e32 v2, v196
	s_movk_i32 s11, 0x420
	v_ashrrev_i32_e32 v36, 1, v52
	v_ashrrev_i32_e32 v37, 31, v36
	s_waitcnt vmcnt(0)
	v_lshlrev_b64 v[4:5], 5, v[36:37]
	v_add_u32_e32 v37, 0x200, v52
	v_ashrrev_i32_e32 v38, 1, v37
	v_ashrrev_i32_e32 v39, 31, v38
	v_lshlrev_b64 v[6:7], 5, v[38:39]
	v_add_u32_e32 v39, 0x400, v52
	v_lshlrev_b32_e32 v2, 4, v52
	v_ashrrev_i32_e32 v40, 1, v39
	v_and_b32_e32 v2, 16, v2
	v_ashrrev_i32_e32 v41, 31, v40
	v_lshl_add_u64 v[32:33], s[74:75], 0, v[2:3]
	v_lshlrev_b64 v[12:13], 5, v[40:41]
	v_add_u32_e32 v41, 0x600, v52
	v_lshl_add_u64 v[4:5], v[32:33], 0, v[4:5]
	v_lshl_add_u64 v[8:9], v[32:33], 0, v[6:7]
	v_ashrrev_i32_e32 v42, 1, v41
	global_load_dwordx4 v[4:7], v[4:5], off
	s_nop 0
	global_load_dwordx4 v[8:11], v[8:9], off
	v_ashrrev_i32_e32 v43, 31, v42
	v_lshl_add_u64 v[12:13], v[32:33], 0, v[12:13]
	v_lshlrev_b64 v[16:17], 5, v[42:43]
	global_load_dwordx4 v[12:15], v[12:13], off
	v_lshl_add_u64 v[16:17], v[32:33], 0, v[16:17]
	v_add_u32_e32 v43, 0x800, v52
	global_load_dwordx4 v[16:19], v[16:17], off
	v_ashrrev_i32_e32 v44, 1, v43
	v_ashrrev_i32_e32 v45, 31, v44
	v_lshlrev_b64 v[20:21], 5, v[44:45]
	v_lshl_add_u64 v[20:21], v[32:33], 0, v[20:21]
	v_add_u32_e32 v45, 0xa00, v52
	global_load_dwordx4 v[20:23], v[20:21], off
	v_ashrrev_i32_e32 v46, 1, v45
	v_ashrrev_i32_e32 v47, 31, v46
	v_lshlrev_b64 v[24:25], 5, v[46:47]
	v_lshl_add_u64 v[24:25], v[32:33], 0, v[24:25]
	v_add_u32_e32 v47, 0xc00, v52
	global_load_dwordx4 v[24:27], v[24:25], off
	v_ashrrev_i32_e32 v48, 1, v47
	v_ashrrev_i32_e32 v49, 31, v48
	v_lshlrev_b64 v[28:29], 5, v[48:49]
	v_lshl_add_u64 v[28:29], v[32:33], 0, v[28:29]
	v_add_u32_e32 v49, 0xe00, v52
	global_load_dwordx4 v[28:31], v[28:29], off
	v_ashrrev_i32_e32 v50, 1, v49
	v_ashrrev_i32_e32 v51, 31, v50
	v_lshlrev_b64 v[34:35], 5, v[50:51]
	v_lshl_add_u64 v[32:33], v[32:33], 0, v[34:35]
	global_load_dwordx4 v[32:35], v[32:33], off
	v_mov_b32_e32 v156, v196
	v_ashrrev_i32_e32 v157, 31, v156
	v_lshl_add_u64 v[156:157], v[156:157], 4, s[72:73]
	v_readlane_b32 s72, v253, 41
	v_readlane_b32 s73, v253, 42
	s_nop 1
	v_lshl_add_u64 v[158:159], v[156:157], 0, s[72:73]
	global_load_dwordx4 v[164:167], v[158:159], off
	v_readlane_b32 s72, v253, 33
	v_readlane_b32 s73, v253, 34
	s_nop 1
	v_lshl_add_u64 v[158:159], v[156:157], 0, s[72:73]
	global_load_dwordx4 v[168:171], v[158:159], off
	v_readlane_b32 s72, v254, 23
	v_readlane_b32 s73, v254, 24
	s_nop 1
	v_lshl_add_u64 v[158:159], v[156:157], 0, s[72:73]
	v_readlane_b32 s72, v253, 43
	v_readlane_b32 s73, v253, 44
	s_nop 1
	v_lshl_add_u64 v[160:161], v[156:157], 0, s[72:73]
	global_load_dwordx4 v[176:179], v[158:159], off
	global_load_dwordx4 v[180:183], v[160:161], off
	v_readlane_b32 s72, v254, 46
	v_readlane_b32 s73, v254, 47
	s_nop 1
	v_lshl_add_u64 v[158:159], v[156:157], 0, s[72:73]
	v_readlane_b32 s72, v253, 31
	v_readlane_b32 s73, v253, 32
	s_nop 1
	v_lshl_add_u64 v[160:161], v[156:157], 0, s[72:73]
	v_readlane_b32 s72, v253, 35
	v_readlane_b32 s73, v253, 36
	global_load_dwordx4 v[184:187], v[158:159], off
	global_load_dwordx4 v[188:191], v[160:161], off
	v_lshl_add_u64 v[158:159], v[156:157], 0, s[72:73]
	v_readlane_b32 s72, v253, 37
	v_readlane_b32 s73, v253, 38
	s_nop 1
	v_lshl_add_u64 v[160:161], v[156:157], 0, s[72:73]
	v_readlane_b32 s72, v254, 19
	v_readlane_b32 s73, v254, 20
	global_load_dwordx4 v[212:215], v[158:159], off
	global_load_dwordx4 v[216:219], v[160:161], off
	v_lshl_add_u64 v[158:159], v[156:157], 0, s[72:73]
	v_readlane_b32 s72, v254, 48
	v_readlane_b32 s73, v254, 49
	s_nop 1
	v_lshl_add_u64 v[160:161], v[156:157], 0, s[72:73]
	v_readlane_b32 s72, v254, 50
	v_readlane_b32 s73, v254, 51
	global_load_dwordx4 v[220:223], v[158:159], off
	global_load_dwordx4 v[224:227], v[160:161], off
	v_lshl_add_u64 v[158:159], v[156:157], 0, s[72:73]
	v_readlane_b32 s72, v253, 39
	v_readlane_b32 s73, v253, 40
	s_nop 1
	v_lshl_add_u64 v[160:161], v[156:157], 0, s[72:73]
	v_readlane_b32 s72, v254, 52
	v_readlane_b32 s73, v254, 53
	global_load_dwordx4 v[228:231], v[158:159], off
	global_load_dwordx4 v[232:235], v[160:161], off
	v_lshl_add_u64 v[158:159], v[156:157], 0, s[72:73]
	v_lshl_add_u64 v[160:161], v[156:157], 0, s[80:81]
	global_load_dwordx4 v[236:239], v[158:159], off
	global_load_dwordx4 v[240:243], v[160:161], off
	v_lshl_add_u64 v[158:159], v[156:157], 0, s[76:77]
	v_lshl_add_u64 v[156:157], v[156:157], 0, s[30:31]
	global_load_dwordx4 v[198:201], v[158:159], off
	s_nop 0
	global_load_dwordx4 v[202:205], v[156:157], off
	v_ashrrev_i32_e32 v51, 6, v52
	v_mul_lo_u32 v51, v51, s11
	v_lshlrev_b32_e32 v36, 5, v36
	v_ashrrev_i32_e32 v37, 6, v37
	v_ashrrev_i32_e32 v39, 6, v39
	v_add_u32_e32 v51, 0, v51
	v_and_b32_e32 v36, 0x3e0, v36
	v_mul_lo_u32 v37, v37, s11
	v_lshlrev_b32_e32 v38, 5, v38
	v_mul_lo_u32 v39, v39, s11
	v_lshlrev_b32_e32 v40, 5, v40
	v_ashrrev_i32_e32 v41, 6, v41
	v_add3_u32 v36, v51, v36, v2
	v_add_u32_e32 v37, 0, v37
	v_and_b32_e32 v38, 0x3e0, v38
	v_add_u32_e32 v39, 0, v39
	v_and_b32_e32 v40, 0x3e0, v40
	v_add3_u32 v37, v37, v38, v2
	v_add3_u32 v38, v39, v40, v2
	s_waitcnt vmcnt(23)
; #define LAS __attribute__((address_space(3)))
; #define S5_LAUNDER() int tid_ = tid0, lane_ = lane0; asm volatile("" : "+v"(tid_), "+v"(lane_)); const int tid = tid_, lane = lane_, fr = lane & 15, fq = lane >> 4; (void)tid; (void)fr; (void)fq
; __device__ __forceinline__ void s5_prompt_item_mfma(LAS unsigned char* lds, int tid0, int lane0, int wave, int n, int g, const bf16* USg, const bf16* FTg, const bf16* WTg, const bf16* GTg, ...
;     ...
;       for (int it = 0; it < 8; ++it) { const int q = tid + 512 * it, token = q >> 1, half = q & 1; const v4u v = *(const v4u*)(usrc + (size_t)token * 16 + 8 * half);
;           *(LAS v4u*)(lds + U_OFF + (token >> 5) * 1056 + (token & 31) * 32 + 16 * half) = v; } }
;     bf16x8 wa[16];
;     { S5_LAUNDER();
; #pragma unroll
;     for (int ks = 0; ks < 16; ++ks) wa[ks] = *(const bf16x8*)(WTg + ((size_t)(wave * 16 + ks) * 64 + lane) * 8);
;     }
;     __syncthreads();
;     {   S5_LAUNDER();
;         f32x4 accS[4];
; #pragma unroll
;         for (int cb = 0; cb < 4; ++cb) accS[cb] = (f32x4){0.f, 0.f, 0.f, 0.f};
; #pragma unroll
;         for (int ks = 0; ks < 16; ++ks) {
; #pragma unroll
;             for (int cb = 0; cb < 4; ++cb) { const bf16x8 b = *(const LAS bf16x8*)(lds + U_OFF + (16 * cb + fr) * 1056 + (2 * ks + (fq >> 1)) * 32 + 16 * (fq & 1));
;                 accS[cb] = __builtin_amdgcn_mfma_f32_16x16x32_bf16(wa[ks], b, accS[cb], 0, 0, 0); }
;             if (ks & 1) asm volatile("" ::: "memory"); }
	ds_write_b128 v36, v[4:7]
	s_waitcnt vmcnt(22)
	ds_write_b128 v37, v[8:11]
	s_waitcnt vmcnt(21)
	ds_write_b128 v38, v[12:15]
	v_mul_lo_u32 v4, v41, s11
	v_lshlrev_b32_e32 v5, 5, v42
	v_add_u32_e32 v4, 0, v4
	v_and_b32_e32 v5, 0x3e0, v5
	v_add3_u32 v4, v4, v5, v2
	s_waitcnt vmcnt(20)
	ds_write_b128 v4, v[16:19]
	v_ashrrev_i32_e32 v4, 6, v43
	v_mul_lo_u32 v4, v4, s11
	v_lshlrev_b32_e32 v5, 5, v44
	v_add_u32_e32 v4, 0, v4
	v_and_b32_e32 v5, 0x3e0, v5
	v_add3_u32 v4, v4, v5, v2
	s_waitcnt vmcnt(19)
	ds_write_b128 v4, v[20:23]
	v_ashrrev_i32_e32 v4, 6, v45
	v_mul_lo_u32 v4, v4, s11
	v_lshlrev_b32_e32 v5, 5, v46
	v_add_u32_e32 v4, 0, v4
	v_and_b32_e32 v5, 0x3e0, v5
	v_add3_u32 v4, v4, v5, v2
	s_waitcnt vmcnt(18)
	ds_write_b128 v4, v[24:27]
	v_ashrrev_i32_e32 v4, 6, v47
	v_mul_lo_u32 v4, v4, s11
	v_lshlrev_b32_e32 v5, 5, v48
	v_add_u32_e32 v4, 0, v4
	v_and_b32_e32 v5, 0x3e0, v5
	v_add3_u32 v4, v4, v5, v2
	s_waitcnt vmcnt(17)
	ds_write_b128 v4, v[28:31]
	v_ashrrev_i32_e32 v4, 6, v49
	v_mul_lo_u32 v4, v4, s11
	v_lshlrev_b32_e32 v5, 5, v50
	v_add_u32_e32 v4, 0, v4
	v_and_b32_e32 v5, 0x3e0, v5
	v_add3_u32 v2, v4, v5, v2
	s_waitcnt vmcnt(16)
	ds_write_b128 v2, v[32:35]
	v_mov_b32_e32 v2, v192
	v_mov_b32_e32 v4, v196
	v_mov_b32_e32 v48, v192
	v_mov_b32_e32 v2, v196
	s_movk_i32 s11, 0x4000
	s_waitcnt lgkmcnt(0)
	s_barrier
	s_nop 0
	v_and_b32_e32 v48, 15, v2
	v_and_b32_e32 v49, 0xffffffe0, v2
	v_add_u32_e32 v49, 0, v49
	v_and_b32_e32 v70, 16, v2
	v_mul_u32_u24_e32 v71, 0x420, v48
	v_add3_u32 v49, v49, v70, v71
	v_and_b32_e32 v2, -16, v2
	ds_read_b128 v[108:111], v49
	ds_read_b128 v[112:115], v49 offset:16896
	ds_read_b128 v[116:119], v49 offset:33792
	ds_read_b128 v[120:123], v49 offset:50688
	ds_read_b128 v[124:127], v49 offset:64
	ds_read_b128 v[128:131], v49 offset:16960
	ds_read_b128 v[132:135], v49 offset:33856
	ds_read_b128 v[136:139], v49 offset:50752
	ds_read_b128 v[140:143], v49 offset:128
	ds_read_b128 v[144:147], v49 offset:17024
	ds_read_b128 v[148:151], v49 offset:33920
	ds_read_b128 v[152:155], v49 offset:50816
	s_waitcnt vmcnt(15) lgkmcnt(8)
	v_mfma_f32_16x16x32_bf16 v[70:73], v[164:167], v[108:111], 0
	v_mfma_f32_16x16x32_bf16 v[74:77], v[164:167], v[112:115], 0
	v_mfma_f32_16x16x32_bf16 v[78:81], v[164:167], v[116:119], 0
	v_mfma_f32_16x16x32_bf16 v[82:85], v[164:167], v[120:123], 0
	ds_read_b128 v[108:111], v49 offset:192
	ds_read_b128 v[112:115], v49 offset:17088
	ds_read_b128 v[116:119], v49 offset:33984
	ds_read_b128 v[120:123], v49 offset:50880
	s_waitcnt vmcnt(14) lgkmcnt(8)
	v_mfma_f32_16x16x32_bf16 v[70:73], v[168:171], v[124:127], v[70:73]
	v_mfma_f32_16x16x32_bf16 v[74:77], v[168:171], v[128:131], v[74:77]
	v_mfma_f32_16x16x32_bf16 v[78:81], v[168:171], v[132:135], v[78:81]
	v_mfma_f32_16x16x32_bf16 v[82:85], v[168:171], v[136:139], v[82:85]
	ds_read_b128 v[124:127], v49 offset:256
	ds_read_b128 v[128:131], v49 offset:17152
	ds_read_b128 v[132:135], v49 offset:34048
	ds_read_b128 v[136:139], v49 offset:50944
	s_waitcnt vmcnt(13) lgkmcnt(8)
	v_mfma_f32_16x16x32_bf16 v[70:73], v[176:179], v[140:143], v[70:73]
	v_mfma_f32_16x16x32_bf16 v[74:77], v[176:179], v[144:147], v[74:77]
	v_mfma_f32_16x16x32_bf16 v[78:81], v[176:179], v[148:151], v[78:81]
	v_mfma_f32_16x16x32_bf16 v[82:85], v[176:179], v[152:155], v[82:85]
	ds_read_b128 v[140:143], v49 offset:320
	ds_read_b128 v[144:147], v49 offset:17216
	ds_read_b128 v[148:151], v49 offset:34112
	ds_read_b128 v[152:155], v49 offset:51008
	s_waitcnt vmcnt(12) lgkmcnt(8)
	v_mfma_f32_16x16x32_bf16 v[70:73], v[180:183], v[108:111], v[70:73]
	v_mfma_f32_16x16x32_bf16 v[74:77], v[180:183], v[112:115], v[74:77]
	v_mfma_f32_16x16x32_bf16 v[78:81], v[180:183], v[116:119], v[78:81]
	v_mfma_f32_16x16x32_bf16 v[82:85], v[180:183], v[120:123], v[82:85]
	ds_read_b128 v[108:111], v49 offset:384
	ds_read_b128 v[112:115], v49 offset:17280
	ds_read_b128 v[116:119], v49 offset:34176
	ds_read_b128 v[120:123], v49 offset:51072
	s_waitcnt vmcnt(11) lgkmcnt(8)
	v_mfma_f32_16x16x32_bf16 v[70:73], v[184:187], v[124:127], v[70:73]
	v_mfma_f32_16x16x32_bf16 v[74:77], v[184:187], v[128:131], v[74:77]
	v_mfma_f32_16x16x32_bf16 v[78:81], v[184:187], v[132:135], v[78:81]
	v_mfma_f32_16x16x32_bf16 v[82:85], v[184:187], v[136:139], v[82:85]
	ds_read_b128 v[124:127], v49 offset:448
	ds_read_b128 v[128:131], v49 offset:17344
	ds_read_b128 v[132:135], v49 offset:34240
	ds_read_b128 v[136:139], v49 offset:51136
	s_waitcnt vmcnt(10) lgkmcnt(8)
	v_mfma_f32_16x16x32_bf16 v[70:73], v[188:191], v[140:143], v[70:73]
	v_mfma_f32_16x16x32_bf16 v[74:77], v[188:191], v[144:147], v[74:77]
	v_mfma_f32_16x16x32_bf16 v[78:81], v[188:191], v[148:151], v[78:81]
	v_mfma_f32_16x16x32_bf16 v[82:85], v[188:191], v[152:155], v[82:85]
	ds_read_b128 v[140:143], v49 offset:512
	ds_read_b128 v[144:147], v49 offset:17408
	ds_read_b128 v[148:151], v49 offset:34304
	ds_read_b128 v[152:155], v49 offset:51200
	s_waitcnt vmcnt(9) lgkmcnt(8)
	v_mfma_f32_16x16x32_bf16 v[70:73], v[212:215], v[108:111], v[70:73]
	v_mfma_f32_16x16x32_bf16 v[74:77], v[212:215], v[112:115], v[74:77]
	v_mfma_f32_16x16x32_bf16 v[78:81], v[212:215], v[116:119], v[78:81]
	v_mfma_f32_16x16x32_bf16 v[82:85], v[212:215], v[120:123], v[82:85]
	ds_read_b128 v[108:111], v49 offset:576
	ds_read_b128 v[112:115], v49 offset:17472
	ds_read_b128 v[116:119], v49 offset:34368
	ds_read_b128 v[120:123], v49 offset:51264
	s_waitcnt vmcnt(8) lgkmcnt(8)
	v_mfma_f32_16x16x32_bf16 v[70:73], v[216:219], v[124:127], v[70:73]
	v_mfma_f32_16x16x32_bf16 v[74:77], v[216:219], v[128:131], v[74:77]
	v_mfma_f32_16x16x32_bf16 v[78:81], v[216:219], v[132:135], v[78:81]
	v_mfma_f32_16x16x32_bf16 v[82:85], v[216:219], v[136:139], v[82:85]
	ds_read_b128 v[124:127], v49 offset:640
	ds_read_b128 v[128:131], v49 offset:17536
	ds_read_b128 v[132:135], v49 offset:34432
	ds_read_b128 v[136:139], v49 offset:51328
	s_waitcnt vmcnt(7) lgkmcnt(8)
; #define LAS __attribute__((address_space(3)))
; #define S5_LAUNDER() int tid_ = tid0, lane_ = lane0; asm volatile("" : "+v"(tid_), "+v"(lane_)); const int tid = tid_, lane = lane_, fr = lane & 15, fq = lane >> 4; (void)tid; (void)fr; (void)fq
; __device__ __forceinline__ void s5_prompt_item_mfma(LAS unsigned char* lds, int tid0, int lane0, int wave, int n, int g, const bf16* USg, const bf16* FTg, const bf16* WTg, const bf16* GTg, ...
;     ...
;         for (int ks = 0; ks < 16; ++ks) {
; #pragma unroll
;             for (int cb = 0; cb < 4; ++cb) { const bf16x8 b = *(const LAS bf16x8*)(lds + U_OFF + (16 * cb + fr) * 1056 + (2 * ks + (fq >> 1)) * 32 + 16 * (fq & 1));
;                 accS[cb] = __builtin_amdgcn_mfma_f32_16x16x32_bf16(wa[ks], b, accS[cb], 0, 0, 0); }
;             if (ks & 1) asm volatile("" ::: "memory"); }
; #pragma unroll
;         for (int cb = 0; cb < 4; ++cb) *(LAS f32x4*)(lds + R2_OFF + ((16 * cb + fr) * 132 + 16 * wave + 4 * fq) * 4) = accS[cb];
;     }
;     __syncthreads();
;     const int tau0 = wave, tau1 = 15 - wave, tau2 = 16 + wave, tau3 = 31 - wave;
;     bf16x8 ga[4][4]; v4u ftq[4];
;     { S5_LAUNDER();
; #pragma unroll
;       for (int it = 0; it < 4; ++it) { const int q = tid + 512 * it; ftq[it] = *(const v4u*)(FTg + (size_t)q * 8); }
; #pragma unroll
;       for (int kk = 0; kk < 4; ++kk) { ga[0][kk] = *(const bf16x8*)(GTg + ((size_t)(tau0 * 4 + kk) * 64 + lane) * 8); ga[1][kk] = *(const bf16x8*)(GTg + ((size_t)(tau1 * 4 + kk) * 64 + lane) * 8);
;                                        ga[2][kk] = *(const bf16x8*)(GTg + ((size_t)(tau2 * 4 + kk) * 64 + lane) * 8); ga[3][kk] = *(const bf16x8*)(GTg + ((size_t)(tau3 * 4 + kk) * 64 + lane) * 8); } }
;     { S5_LAUNDER(); if (tid < 64) {
;         const int p = tid; const float lr = ltp[2 * p], li = ltp[2 * p + 1]; float hr = 0.f, hi = 0.f;
	v_mfma_f32_16x16x32_bf16 v[70:73], v[220:223], v[140:143], v[70:73]
	v_mfma_f32_16x16x32_bf16 v[74:77], v[220:223], v[144:147], v[74:77]
	v_mfma_f32_16x16x32_bf16 v[78:81], v[220:223], v[148:151], v[78:81]
	v_mfma_f32_16x16x32_bf16 v[82:85], v[220:223], v[152:155], v[82:85]
	ds_read_b128 v[140:143], v49 offset:704
	ds_read_b128 v[144:147], v49 offset:17600
	ds_read_b128 v[148:151], v49 offset:34496
	ds_read_b128 v[152:155], v49 offset:51392
	s_waitcnt vmcnt(6) lgkmcnt(8)
	v_mfma_f32_16x16x32_bf16 v[70:73], v[224:227], v[108:111], v[70:73]
	v_mfma_f32_16x16x32_bf16 v[74:77], v[224:227], v[112:115], v[74:77]
	v_mfma_f32_16x16x32_bf16 v[78:81], v[224:227], v[116:119], v[78:81]
	v_mfma_f32_16x16x32_bf16 v[82:85], v[224:227], v[120:123], v[82:85]
	ds_read_b128 v[108:111], v49 offset:768
	ds_read_b128 v[112:115], v49 offset:17664
	ds_read_b128 v[116:119], v49 offset:34560
	ds_read_b128 v[120:123], v49 offset:51456
	s_waitcnt vmcnt(5) lgkmcnt(8)
	v_mfma_f32_16x16x32_bf16 v[70:73], v[228:231], v[124:127], v[70:73]
	v_mfma_f32_16x16x32_bf16 v[74:77], v[228:231], v[128:131], v[74:77]
	v_mfma_f32_16x16x32_bf16 v[78:81], v[228:231], v[132:135], v[78:81]
	v_mfma_f32_16x16x32_bf16 v[82:85], v[228:231], v[136:139], v[82:85]
	ds_read_b128 v[124:127], v49 offset:832
	ds_read_b128 v[128:131], v49 offset:17728
	ds_read_b128 v[132:135], v49 offset:34624
	ds_read_b128 v[136:139], v49 offset:51520
	s_waitcnt vmcnt(4) lgkmcnt(8)
	v_mfma_f32_16x16x32_bf16 v[70:73], v[232:235], v[140:143], v[70:73]
	v_mfma_f32_16x16x32_bf16 v[74:77], v[232:235], v[144:147], v[74:77]
	v_mfma_f32_16x16x32_bf16 v[78:81], v[232:235], v[148:151], v[78:81]
	v_mfma_f32_16x16x32_bf16 v[82:85], v[232:235], v[152:155], v[82:85]
	ds_read_b128 v[140:143], v49 offset:896
	ds_read_b128 v[144:147], v49 offset:17792
	ds_read_b128 v[148:151], v49 offset:34688
	ds_read_b128 v[152:155], v49 offset:51584
	s_waitcnt vmcnt(3) lgkmcnt(8)
	v_mfma_f32_16x16x32_bf16 v[70:73], v[236:239], v[108:111], v[70:73]
	v_mfma_f32_16x16x32_bf16 v[74:77], v[236:239], v[112:115], v[74:77]
	v_mfma_f32_16x16x32_bf16 v[78:81], v[236:239], v[116:119], v[78:81]
	v_mfma_f32_16x16x32_bf16 v[82:85], v[236:239], v[120:123], v[82:85]
	ds_read_b128 v[108:111], v49 offset:960
	ds_read_b128 v[112:115], v49 offset:17856
	ds_read_b128 v[116:119], v49 offset:34752
	ds_read_b128 v[120:123], v49 offset:51648
	s_waitcnt vmcnt(2) lgkmcnt(8)
	v_mfma_f32_16x16x32_bf16 v[70:73], v[240:243], v[124:127], v[70:73]
	v_mfma_f32_16x16x32_bf16 v[74:77], v[240:243], v[128:131], v[74:77]
	v_mfma_f32_16x16x32_bf16 v[78:81], v[240:243], v[132:135], v[78:81]
	v_mfma_f32_16x16x32_bf16 v[82:85], v[240:243], v[136:139], v[82:85]
	s_waitcnt vmcnt(1) lgkmcnt(4)
	v_mfma_f32_16x16x32_bf16 v[70:73], v[198:201], v[140:143], v[70:73]
	v_mfma_f32_16x16x32_bf16 v[74:77], v[198:201], v[144:147], v[74:77]
	v_mfma_f32_16x16x32_bf16 v[78:81], v[198:201], v[148:151], v[78:81]
	v_mfma_f32_16x16x32_bf16 v[82:85], v[198:201], v[152:155], v[82:85]
	s_waitcnt vmcnt(0) lgkmcnt(0)
	v_mfma_f32_16x16x32_bf16 v[70:73], v[202:205], v[108:111], v[70:73]
	v_mfma_f32_16x16x32_bf16 v[74:77], v[202:205], v[112:115], v[74:77]
	v_mfma_f32_16x16x32_bf16 v[78:81], v[202:205], v[116:119], v[78:81]
	v_mfma_f32_16x16x32_bf16 v[82:85], v[202:205], v[120:123], v[82:85]
	s_nop 7
	v_mul_u32_u24_e32 v8, 0x210, v48
	v_add3_u32 v2, s36, v2, v8
	ds_write_b128 v2, v[70:73]
	ds_write_b128 v2, v[74:77] offset:8448
	ds_write_b128 v2, v[78:81] offset:16896
	ds_write_b128 v2, v[82:85] offset:25344
	v_mov_b32_e32 v4, v192
	v_mov_b32_e32 v6, v196
	s_waitcnt lgkmcnt(0)
	s_barrier
	v_mov_b32_e32 v2, v196
	v_ashrrev_i32_e32 v5, 31, v4
	v_lshl_add_u64 v[4:5], v[4:5], 4, vcc
	v_add_co_u32_e32 v8, vcc, s33, v4
	v_ashrrev_i32_e32 v7, 31, v6
	s_nop 0
	v_addc_co_u32_e32 v9, vcc, 0, v5, vcc
	v_add_co_u32_e32 v10, vcc, s11, v4
	s_movk_i32 s11, 0x6000
	s_nop 0
	v_addc_co_u32_e32 v11, vcc, 0, v5, vcc
	v_add_co_u32_e32 v12, vcc, s11, v4
	v_lshl_add_u64 v[6:7], v[6:7], 4, s[54:55]
	s_nop 0
	v_addc_co_u32_e32 v13, vcc, 0, v5, vcc
	global_load_dwordx4 v[24:27], v[4:5], off
	global_load_dwordx4 v[28:31], v[8:9], off
	global_load_dwordx4 v[32:35], v[10:11], off
	global_load_dwordx4 v[36:39], v[12:13], off
	v_lshl_add_u64 v[4:5], v[6:7], 0, s[34:35]
	v_lshl_add_u64 v[8:9], v[6:7], 0, s[38:39]
	global_load_dwordx4 v[152:155], v[4:5], off
	global_load_dwordx4 v[124:127], v[8:9], off
	v_lshl_add_u64 v[4:5], v[6:7], 0, s[2:3]
	v_lshl_add_u64 v[8:9], v[6:7], 0, s[0:1]
	global_load_dwordx4 v[108:111], v[4:5], off
	global_load_dwordx4 v[16:19], v[8:9], off
	v_lshl_add_u64 v[4:5], v[6:7], 0, s[4:5]
	v_lshl_add_u64 v[8:9], v[6:7], 0, s[28:29]
	global_load_dwordx4 v[140:143], v[4:5], off
	global_load_dwordx4 v[128:131], v[8:9], off
	v_lshl_add_u64 v[4:5], v[6:7], 0, s[18:19]
	v_lshl_add_u64 v[8:9], v[6:7], 0, s[92:93]
	global_load_dwordx4 v[112:115], v[4:5], off
	global_load_dwordx4 v[12:15], v[8:9], off
	v_lshl_add_u64 v[4:5], v[6:7], 0, s[96:97]
	v_lshl_add_u64 v[8:9], v[6:7], 0, s[40:41]
	global_load_dwordx4 v[144:147], v[4:5], off
	global_load_dwordx4 v[132:135], v[8:9], off
	v_lshl_add_u64 v[4:5], v[6:7], 0, s[42:43]
	v_lshl_add_u64 v[8:9], v[6:7], 0, s[44:45]
	global_load_dwordx4 v[116:119], v[4:5], off
	s_nop 0
	global_load_dwordx4 v[8:11], v[8:9], off
	v_lshl_add_u64 v[4:5], v[6:7], 0, s[46:47]
	v_lshl_add_u64 v[20:21], v[6:7], 0, s[48:49]
	global_load_dwordx4 v[148:151], v[4:5], off
	global_load_dwordx4 v[136:139], v[20:21], off
	v_lshl_add_u64 v[4:5], v[6:7], 0, s[50:51]
	v_lshl_add_u64 v[6:7], v[6:7], 0, s[88:89]
	global_load_dwordx4 v[120:123], v[4:5], off
	s_nop 0
	global_load_dwordx4 v[4:7], v[6:7], off
	v_mov_b32_e32 v20, v192
	s_nop 0
	v_cmp_gt_i32_e32 vcc, 64, v20
	s_and_saveexec_b64 s[54:55], vcc
	s_cbranch_execz .LBB0_852
	v_readlane_b32 s72, v254, 32
	s_or_b32 s11, s72, s65
	s_mulk_i32 s11, 0x4200
	v_readlane_b32 s72, v253, 63
	v_readlane_b32 s73, v254, 33
	s_add_u32 s72, s72, s11
	v_readlane_b32 s11, v254, 1
	v_lshlrev_b32_e32 v22, 1, v20
	s_addc_u32 s73, s11, 0
	v_ashrrev_i32_e32 v23, 31, v22
	v_lshl_add_u64 v[22:23], v[22:23], 2, s[72:73]
	global_load_dwordx2 v[22:23], v[22:23], off
	v_mov_b32_e32 v42, 0
	v_lshlrev_b32_e32 v2, 2, v20
	v_lshlrev_b32_e32 v21, 3, v20
	s_mov_b32 s11, 64
	v_mov_b32_e32 v43, v42
	s_waitcnt vmcnt(0)
	v_pk_mov_b32 v[40:41], v[22:23], v[22:23] op_sel:[1,0]
	v_add_u32_e32 v84, 0x10800, v21
	ds_read_b64 v[68:69], v84
	ds_read_b64 v[70:71], v84 offset:528
	ds_read_b64 v[72:73], v84 offset:1056
	ds_read_b64 v[74:75], v84 offset:1584
	ds_read_b64 v[76:77], v84 offset:2112
	ds_read_b64 v[78:79], v84 offset:2640
	ds_read_b64 v[80:81], v84 offset:3168
	ds_read_b64 v[82:83], v84 offset:3696

; #define GPTR(T, p) gptr_<T>(p)
; #define GIN(i) GPTR(const float, args.in[i])
; __device__ __forceinline__ void s5_sample_wave(int lane, int b, int g, const float* tb, const float* cre, const float* cim, const float* dsk,
;                                                const bf16* US, bf16* YS, const float* st_re, const float* st_im, float* out_re, float* out_im) {
;     ...
;     const int ho = ((lane >> 5) & 1) * 8 + ((lane >> 4) & 1) * 4 + ((lane >> 3) & 1) * 2 + ((lane >> 2) & 1);
;     const bf16* up0 = US + ((size_t)g * M + MP + (size_t)b * DECS) * 16;
; __global__ void __launch_bounds__(NWAVES * 64, 2) hymba_fwd(Args args) {
;     ...
;             for (int it = bx * NWAVES + wave; it < DECB * NG; it += G * NWAVES) { const int g = it & 31, b = it >> 5;
;                 s5_sample_wave(lane, b, g, tb, cre, cim, dsk, US, YS, GIN(I_STRE) + (size_t)L * DECB * NG * NP, GIN(I_STIM) + (size_t)L * DECB * NG * NP,
;                                GPTR(float, args.out) + O_RES + (size_t)L * DECB * NG * NP, GPTR(float, args.out) + O_IMS + (size_t)L * DECB * NG * NP); }
.LBB0_890:
	v_readlane_b32 s61, v254, 12
	s_add_i32 s2, s56, s61
	v_readlane_b32 s64, v254, 9
	v_readlane_b32 s72, v254, 38
	v_readlane_b32 s78, v254, 17
	v_readlane_b32 s80, v254, 21
	v_readlane_b32 s88, v255, 6
	v_readlane_b32 s92, v255, 8
	s_cmpk_gt_i32 s2, 0xfff
	v_readlane_b32 s65, v254, 10
	v_readlane_b32 s73, v254, 39
	v_readlane_b32 s76, v254, 40
	v_readlane_b32 s79, v254, 18
	v_readlane_b32 s81, v254, 22
	v_readlane_b32 s82, v254, 25
	v_readlane_b32 s83, v255, 5
	v_readlane_b32 s89, v255, 7
	v_readlane_b32 s93, v255, 9
	v_readlane_b32 s77, v254, 41
	s_cbranch_scc1 .LBB0_901
	v_readlane_b32 s0, v255, 3
	v_readlane_b32 s4, v254, 5
	v_readlane_b32 s1, v255, 4
	v_readlane_b32 s5, v254, 6
	s_add_u32 s18, s4, s0
	s_addc_u32 s19, s5, s1
	v_readlane_b32 s4, v254, 3
	v_readlane_b32 s5, v254, 4
	s_add_u32 s20, s4, s0
	v_and_b32_e32 v2, 16, v192
	s_addc_u32 s21, s5, s1
	v_cmp_eq_u32_e64 s[4:5], 0, v2
	v_and_b32_e32 v2, 8, v192
	s_ashr_i32 s3, s2, 31
	v_cmp_eq_u32_e64 s[6:7], 0, v2
	v_and_b32_e32 v2, 4, v192
	s_lshl_b64 s[12:13], s[2:3], 8
	v_readlane_b32 s14, v254, 63
	v_lshrrev_b32_e32 v44, 2, v196
	v_cmp_eq_u32_e64 s[8:9], 0, v2
	v_and_b32_e32 v2, 3, v192
	v_readlane_b32 s15, v255, 0
	s_add_u32 s12, s14, s12
	v_cmp_eq_u32_e64 s[10:11], 0, v2
	v_lshlrev_b32_e32 v2, 1, v44
	s_addc_u32 s13, s15, s13
	v_lshlrev_b32_e32 v48, 2, v196
	v_mov_b32_e32 v49, v3
	v_cmp_gt_u32_e64 s[0:1], 32, v196
	v_lshl_add_u64 v[46:47], s[22:23], 0, v[2:3]
	v_lshl_add_u64 v[50:51], s[12:13], 0, v[48:49]
	s_waitcnt vmcnt(0)
	s_branch .LBB0_893

; __device__ __forceinline__ float bflo(unsigned w) { return __uint_as_float(w << 16); }
; __device__ __forceinline__ float bfhi(unsigned w) { return __uint_as_float(w & 0xffff0000u); }
; __device__ __forceinline__ void s5_sample_wave(int lane, int b, int g, const float* tb, const float* cre, const float* cim, const float* dsk,
;                                                const bf16* US, bf16* YS, const float* st_re, const float* st_im, float* out_re, float* out_im) {
;     const int p = lane, gp = g * 64 + p;
;     const float ar = tb[gp], ai = tb[2048 + gp];
;     float bbr[16], bbi[16], cr[16], ci[16];
; #pragma unroll
;     for (int q = 0; q < 4; ++q) { const f32x4 a = *(const f32x4*)(tb + 4096 + gp * 16 + 4 * q), c = *(const f32x4*)(tb + 4096 + 32768 + gp * 16 + 4 * q);
; #pragma unroll
;         for (int j = 0; j < 4; ++j) { bbr[4 * q + j] = a[j]; bbi[4 * q + j] = c[j]; } }
; #pragma unroll
;     for (int h = 0; h < 16; ++h) { cr[h] = cre[(size_t)(g * 16 + h) * 64 + p]; ci[h] = cim[(size_t)(g * 16 + h) * 64 + p]; }
;     float hr = st_re[(size_t)(b * NG + g) * NP + p], hi = st_im[(size_t)(b * NG + g) * NP + p];
;     const int ho = ((lane >> 5) & 1) * 8 + ((lane >> 4) & 1) * 4 + ((lane >> 3) & 1) * 2 + ((lane >> 2) & 1);
;     const bf16* up0 = US + ((size_t)g * M + MP + (size_t)b * DECS) * 16;
;     v4u qa[DECS], qb[DECS]; float uho[DECS];
; #pragma unroll
;     for (int j = 0; j < DECS; ++j) { qa[j] = *(const v4u*)(up0 + 16 * j); qb[j] = *(const v4u*)(up0 + 16 * j + 8); uho[j] = bf1(up0[16 * j + ho]); }
;     const float dkh = dsk[g * 16 + ho];
; #pragma unroll
;     for (int j = 0; j < DECS; ++j) {
;         const size_t row = (size_t)MP + b * DECS + j;
;         const v4u q0 = qa[j], q1 = qb[j];
;         float u[16];
;         u[0] = bflo(q0.x); u[1] = bfhi(q0.x); u[2] = bflo(q0.y); u[3] = bfhi(q0.y); u[4] = bflo(q0.z); u[5] = bfhi(q0.z); u[6] = bflo(q0.w); u[7] = bfhi(q0.w);
;         u[8] = bflo(q1.x); u[9] = bfhi(q1.x); u[10] = bflo(q1.y); u[11] = bfhi(q1.y); u[12] = bflo(q1.z); u[13] = bfhi(q1.z); u[14] = bflo(q1.w); u[15] = bfhi(q1.w);
;         float br = 0.f, bi = 0.f;
; #pragma unroll
;         for (int h = 0; h < 16; ++h) { br += bbr[h] * u[h]; bi += bbi[h] * u[h]; }
;         const float nr = ar * hr - ai * hi + br, ni = ar * hi + ai * hr + bi; hr = nr; hi = ni;
.LBB0_893:
	s_ashr_i32 s12, s2, 5
	v_readlane_b32 s36, v252, 10
	v_readlane_b32 s24, v252, 4
	s_and_b32 s58, s2, 31
	v_readlane_b32 s42, v252, 16
	v_readlane_b32 s43, v252, 17
	v_readlane_b32 s25, v252, 5
	s_ashr_i32 s13, s12, 31
	s_mov_b64 s[34:35], s[42:43]
	s_mov_b64 s[30:31], s[24:25]
	s_mov_b64 s[28:29], s[24:25]
	s_lshl_b32 s42, s58, 6
	s_lshl_b64 s[24:25], s[12:13], 7
	s_add_u32 s3, s74, s24
	s_addc_u32 s13, s75, s25
	s_mul_i32 s24, s58, 0x84000
	s_add_u32 s24, s3, s24
	v_readlane_b32 s40, v252, 14
	v_readlane_b32 s41, v252, 15
	s_addc_u32 s25, s13, 0
	s_mov_b64 s[14:15], s[40:41]
	s_add_u32 s40, s24, 0x80000
	v_readlane_b32 s26, v252, 6
	s_addc_u32 s41, s25, 0
	v_readlane_b32 s27, v252, 7
	s_add_u32 s26, s24, 0x80040
	v_or_b32_e32 v4, s42, v196
	s_addc_u32 s27, s25, 0
	v_lshlrev_b32_e32 v2, 2, v4
	global_load_dwordx4 v[40:43], v246, s[24:25] offset:64
	global_load_dwordx4 v[90:93], v3, s[26:27] offset:48
	global_load_dwordx4 v[94:97], v3, s[26:27] offset:32
	global_load_dwordx4 v[98:101], v3, s[26:27] offset:16
	v_lshl_or_b32 v36, s58, 12, v48
	global_load_dwordx4 v[102:105], v246, s[24:25]
	global_load_dword v67, v36, s[18:19]
	global_load_dword v63, v36, s[18:19] offset:256
	global_load_dword v60, v36, s[18:19] offset:512
	global_load_dword v56, v36, s[18:19] offset:768
	global_load_dword v55, v36, s[18:19] offset:1024
	global_load_dword v54, v36, s[18:19] offset:1280
	global_load_dword v49, v36, s[18:19] offset:1536
	global_load_dword v45, v36, s[18:19] offset:1792
	v_lshlrev_b32_e32 v24, 6, v4
	global_load_dword v74, v2, s[72:73]
	global_load_dwordx4 v[106:109], v3, s[40:41] offset:16
	global_load_dwordx4 v[4:7], v24, s[68:69] offset:48
	global_load_dwordx4 v[28:31], v24, s[70:71]
	v_lshl_add_u64 v[8:9], s[72:73], 0, v[2:3]
	v_add_co_u32_e32 v8, vcc, s33, v8
	v_lshl_add_u64 v[38:39], s[34:35], 0, v[50:51]
	s_nop 0
	v_addc_co_u32_e32 v9, vcc, 0, v9, vcc
	global_load_dword v77, v[8:9], off
	global_load_dwordx4 v[32:35], v24, s[68:69]
	s_nop 0
	global_load_dwordx4 v[8:11], v24, s[68:69] offset:32
	global_load_dwordx4 v[16:19], v24, s[68:69] offset:16
	global_load_dwordx4 v[12:15], v24, s[70:71] offset:32
	global_load_dwordx4 v[20:23], v24, s[70:71] offset:16
	global_load_dword v83, v36, s[20:21]
	global_load_dword v80, v36, s[20:21] offset:256
	global_load_dword v76, v36, s[20:21] offset:512
	global_load_dword v72, v36, s[20:21] offset:768
	global_load_dword v69, v36, s[20:21] offset:1024
	global_load_dword v65, v36, s[20:21] offset:1280
	global_load_dword v62, v36, s[20:21] offset:1536
	global_load_dword v57, v36, s[20:21] offset:1792
	global_load_dword v85, v36, s[18:19] offset:2048
	global_load_dword v82, v36, s[18:19] offset:2304
	global_load_dword v79, v36, s[18:19] offset:2560
	global_load_dword v75, v36, s[18:19] offset:2816
	global_load_dword v71, v36, s[18:19] offset:3072
	global_load_dword v68, v36, s[18:19] offset:3328
	global_load_dword v64, v36, s[18:19] offset:3584
	global_load_dword v61, v36, s[18:19] offset:3840
	s_nop 0
	global_load_dwordx4 v[24:27], v24, s[70:71] offset:48
	s_nop 0
	global_load_dword v87, v36, s[20:21] offset:2048
	global_load_dword v86, v36, s[20:21] offset:2304
	global_load_dword v84, v36, s[20:21] offset:2560
	global_load_dword v81, v36, s[20:21] offset:2816
	global_load_dword v78, v36, s[20:21] offset:3072
	global_load_dword v73, v36, s[20:21] offset:3328
	global_load_dword v70, v36, s[20:21] offset:3584
	global_load_dword v66, v36, s[20:21] offset:3840
	v_lshl_add_u64 v[36:37], s[14:15], 0, v[50:51]
	global_load_dword v110, v[38:39], off
	global_load_dword v111, v[36:37], off
	v_readlane_b32 s45, v252, 19
	v_readlane_b32 s46, v252, 20
	v_readlane_b32 s49, v252, 23
	v_readlane_b32 s51, v252, 25
	v_readlane_b32 s44, v252, 18
	v_readlane_b32 s47, v252, 21
	v_readlane_b32 s48, v252, 22
	v_readlane_b32 s50, v252, 24
	v_lshlrev_b32_e32 v2, 1, v44
	global_load_dwordx4 v[36:39], v3, s[40:41] offset:32
	global_load_ushort v89, v2, s[40:41] offset:32
	v_lshl_or_b32 v52, v44, 2, s42
	s_lshl_b32 s34, s12, 2
	s_lshl_b32 s84, s58, 5
	s_ashr_i32 s35, s34, 31
	v_readlane_b32 s37, v252, 11
	v_readlane_b32 s38, v252, 12
	v_readlane_b32 s39, v252, 13
	s_waitcnt vmcnt(0)
	v_readfirstlane_b32 s26, v90
	v_lshlrev_b32_e32 v90, 16, v102
	v_readfirstlane_b32 s25, v91
	v_readfirstlane_b32 s45, v95
	v_readfirstlane_b32 s46, v94
	v_readfirstlane_b32 s49, v101
	v_readfirstlane_b32 s51, v100
	v_and_b32_e32 v91, 0xffff0000, v102
	v_lshlrev_b32_e32 v94, 16, v103
	v_and_b32_e32 v95, 0xffff0000, v103
	v_lshlrev_b32_e32 v100, 16, v106
	v_and_b32_e32 v101, 0xffff0000, v106
	v_lshlrev_b32_e32 v102, 16, v107
	v_and_b32_e32 v103, 0xffff0000, v107
	v_lshlrev_b32_e32 v106, 16, v109
	v_and_b32_e32 v107, 0xffff0000, v109
	v_fma_f32 v109, v28, v90, 0
	v_readfirstlane_b32 s27, v97
	v_readfirstlane_b32 s44, v96
	v_readfirstlane_b32 s55, v99
	v_readfirstlane_b32 s57, v98
	v_lshlrev_b32_e32 v96, 16, v104
	v_and_b32_e32 v97, 0xffff0000, v104
	v_lshlrev_b32_e32 v98, 16, v105
	v_and_b32_e32 v99, 0xffff0000, v105
	v_lshlrev_b32_e32 v104, 16, v108
	v_and_b32_e32 v105, 0xffff0000, v108
	v_fma_f32 v108, v32, v90, 0
	v_fmac_f32_e32 v109, v29, v91
	v_fmac_f32_e32 v108, v33, v91
	v_fmac_f32_e32 v109, v30, v94
	v_fmac_f32_e32 v108, v34, v94
	v_fmac_f32_e32 v109, v31, v95
	v_readfirstlane_b32 s47, v43
	v_readfirstlane_b32 s48, v42
	v_readfirstlane_b32 s50, v41
	v_readfirstlane_b32 s54, v40
	global_load_dwordx4 v[40:43], v3, s[40:41] offset:48
	global_load_ushort v88, v2, s[40:41] offset:64
	global_load_ushort v59, v2, s[40:41] offset:96
	v_fmac_f32_e32 v108, v35, v95
	v_fmac_f32_e32 v109, v20, v96
	global_load_dword v58, v52, s[52:53]
; __device__ __forceinline__ float gelu_tanh(float x) { const float u = 1.5957691216057308f * (x + 0.044715f * x * x * x); return x * sigmoid_f(u); }
; __device__ __forceinline__ unsigned f2bf(float f) { unsigned u = __builtin_bit_cast(unsigned, f); return (u + 0x7fffu + ((u >> 16) & 1u)) >> 16; }
; __device__ __forceinline__ void s5_sample_wave(int lane, int b, int g, const float* tb, const float* cre, const float* cim, const float* dsk,
;                                                const bf16* US, bf16* YS, const float* st_re, const float* st_im, float* out_re, float* out_im) {
;     ...
;         float br = 0.f, bi = 0.f;
; #pragma unroll
;         for (int h = 0; h < 16; ++h) { br += bbr[h] * u[h]; bi += bbi[h] * u[h]; }
;         const float nr = ar * hr - ai * hi + br, ni = ar * hi + ai * hr + bi; hr = nr; hi = ni;
;         float v8[8], v4[4], v2[2], v1;
; #pragma unroll
;         for (int h = 0; h < 8; ++h) { const float lo = cr[h] * hr - ci[h] * hi, hi8 = cr[h + 8] * hr - ci[h + 8] * hi; const bool up5 = (lane & 32) != 0;
;             const float keep = up5 ? hi8 : lo, send = up5 ? lo : hi8; v8[h] = keep + fshx<32>(send); }
; #pragma unroll
;         for (int h = 0; h < 4; ++h) { const bool b = (lane & 16) != 0; const float keep = b ? v8[h + 4] : v8[h], send = b ? v8[h] : v8[h + 4]; v4[h] = keep + fshx<16>(send); }
; #pragma unroll
;         for (int h = 0; h < 2; ++h) { const bool b = (lane & 8) != 0; const float keep = b ? v4[h + 2] : v4[h], send = b ? v4[h] : v4[h + 2]; v2[h] = keep + fshx<8>(send); }
;         { const bool b = (lane & 4) != 0; const float keep = b ? v2[1] : v2[0], send = b ? v2[0] : v2[1]; v1 = keep + fshx<4>(send); }
;         v1 += fshx<2>(v1); v1 += fshx<1>(v1);
;         const float yv = v1 + dkh * uho[j];
;         if ((lane & 3) == 0) YS[row * SSMW + g * 16 + ho] = (bf16)f2bf(gelu_tanh(yv));
	v_fmac_f32_e32 v108, v16, v96
	v_fmac_f32_e32 v109, v21, v97
	v_fmac_f32_e32 v108, v17, v97
	v_fmac_f32_e32 v109, v22, v98
	v_fmac_f32_e32 v108, v18, v98
	v_fmac_f32_e32 v109, v23, v99
	v_fmac_f32_e32 v108, v19, v99
	v_fmac_f32_e32 v109, v12, v100
	v_fmac_f32_e32 v108, v8, v100
	v_fmac_f32_e32 v109, v13, v101
	v_fmac_f32_e32 v108, v9, v101
	v_fmac_f32_e32 v109, v14, v102
	v_fmac_f32_e32 v108, v10, v102
	v_fmac_f32_e32 v109, v15, v103
	v_fmac_f32_e32 v108, v11, v103
	v_fmac_f32_e32 v109, v24, v104
	v_fmac_f32_e32 v108, v4, v104
	v_fmac_f32_e32 v109, v25, v105
	v_fmac_f32_e32 v108, v5, v105
	v_fmac_f32_e32 v109, v26, v106
	v_mul_f32_e32 v91, v74, v110
	v_fmac_f32_e32 v108, v6, v106
	v_fmac_f32_e32 v109, v27, v107
	v_mul_f32_e32 v90, v77, v110
	v_fmac_f32_e32 v91, v77, v111
	v_fmac_f32_e32 v108, v7, v107
	v_fma_f32 v90, v74, v111, -v90
	v_add_f32_e32 v91, v91, v109
	v_add_f32_e32 v90, v90, v108
	v_mul_f32_e32 v94, v83, v91
	v_mul_f32_e32 v95, v87, v91
	v_fma_f32 v94, v67, v90, -v94
	v_fma_f32 v95, v85, v90, -v95
	v_cndmask_b32_e64 v96, v95, v94, s[0:1]
	v_cndmask_b32_e64 v94, v94, v95, s[0:1]
	v_readfirstlane_b32 s24, v92
	v_and_b32_e32 v92, 32, v247
	v_mov_b32_e32 v95, v94
	s_nop 1
	v_permlane32_swap_b32_e32 v94, v95
	v_cmp_eq_u32_e64 s[12:13], 0, v92
	v_readfirstlane_b32 s3, v93
	v_and_b32_e32 v93, 16, v247
	v_cndmask_b32_e64 v92, v94, v95, s[12:13]
	v_mul_f32_e32 v94, v80, v91
	v_mul_f32_e32 v95, v86, v91
	v_fma_f32 v94, v63, v90, -v94
	v_fma_f32 v95, v82, v90, -v95
	v_add_f32_e32 v92, v96, v92
	v_cndmask_b32_e64 v96, v95, v94, s[0:1]
	v_cndmask_b32_e64 v94, v94, v95, s[0:1]
	v_mov_b32_e32 v95, v94
	s_nop 1
	v_permlane32_swap_b32_e32 v94, v95
	v_cndmask_b32_e64 v94, v94, v95, s[12:13]
	v_add_f32_e32 v94, v96, v94
	v_mul_f32_e32 v95, v76, v91
	v_mul_f32_e32 v96, v84, v91
	v_fma_f32 v95, v60, v90, -v95
	v_fma_f32 v96, v79, v90, -v96
	v_cndmask_b32_e64 v97, v96, v95, s[0:1]
	v_cndmask_b32_e64 v95, v95, v96, s[0:1]
	v_mov_b32_e32 v96, v95
	s_nop 1
	v_permlane32_swap_b32_e32 v95, v96
	v_cndmask_b32_e64 v95, v95, v96, s[12:13]
	v_add_f32_e32 v95, v97, v95
	v_mul_f32_e32 v96, v72, v91
	v_mul_f32_e32 v97, v81, v91
	v_fma_f32 v96, v56, v90, -v96
	v_fma_f32 v97, v75, v90, -v97
	v_cndmask_b32_e64 v98, v97, v96, s[0:1]
	v_cndmask_b32_e64 v96, v96, v97, s[0:1]
	v_mov_b32_e32 v97, v96
	s_nop 1
	v_permlane32_swap_b32_e32 v96, v97
	v_cndmask_b32_e64 v96, v96, v97, s[12:13]
	v_add_f32_e32 v96, v98, v96
	v_mul_f32_e32 v97, v69, v91
	v_mul_f32_e32 v98, v78, v91
	v_fma_f32 v97, v55, v90, -v97
	v_fma_f32 v98, v71, v90, -v98
	v_cndmask_b32_e64 v99, v98, v97, s[0:1]
	v_cndmask_b32_e64 v97, v97, v98, s[0:1]
	v_mov_b32_e32 v98, v97
	s_nop 1
	v_permlane32_swap_b32_e32 v97, v98
	v_cndmask_b32_e64 v97, v97, v98, s[12:13]
	v_add_f32_e32 v97, v99, v97
	v_mul_f32_e32 v98, v65, v91
	v_mul_f32_e32 v99, v73, v91
	v_fma_f32 v98, v54, v90, -v98
	v_fma_f32 v99, v68, v90, -v99
	v_cndmask_b32_e64 v100, v99, v98, s[0:1]
	v_cndmask_b32_e64 v98, v98, v99, s[0:1]
	v_mov_b32_e32 v99, v98
	s_nop 1
	v_permlane32_swap_b32_e32 v98, v99
	v_cndmask_b32_e64 v98, v98, v99, s[12:13]
	v_add_f32_e32 v98, v100, v98
	v_mul_f32_e32 v99, v62, v91
	v_mul_f32_e32 v100, v70, v91
	v_fma_f32 v99, v49, v90, -v99
	v_fma_f32 v100, v64, v90, -v100
	v_cndmask_b32_e64 v101, v100, v99, s[0:1]
	v_cndmask_b32_e64 v99, v99, v100, s[0:1]
	v_mov_b32_e32 v100, v99
	s_nop 1
	v_permlane32_swap_b32_e32 v99, v100
	v_cndmask_b32_e64 v99, v99, v100, s[12:13]
	v_add_f32_e32 v99, v101, v99
	v_mul_f32_e32 v100, v57, v91
	v_mul_f32_e32 v101, v66, v91
	v_fma_f32 v100, v45, v90, -v100
	v_fma_f32 v101, v61, v90, -v101
	v_cndmask_b32_e64 v102, v101, v100, s[0:1]
	v_cndmask_b32_e64 v100, v100, v101, s[0:1]
	v_mov_b32_e32 v101, v100
	s_nop 1
	v_permlane32_swap_b32_e32 v100, v101
	v_cndmask_b32_e64 v100, v100, v101, s[12:13]
	v_cndmask_b32_e64 v101, v97, v92, s[4:5]
	v_cndmask_b32_e64 v92, v92, v97, s[4:5]
	v_mov_b32_e32 v97, v92
	s_nop 1
	v_permlane16_swap_b32_e32 v92, v97
	v_cmp_eq_u32_e64 s[14:15], 0, v93
	v_cndmask_b32_e64 v93, v98, v94, s[4:5]
	v_cndmask_b32_e64 v94, v94, v98, s[4:5]
	v_cndmask_b32_e64 v92, v92, v97, s[14:15]
	v_mov_b32_e32 v97, v94
	s_nop 1
	v_permlane16_swap_b32_e32 v94, v97
	v_cndmask_b32_e64 v94, v94, v97, s[14:15]
	v_add_f32_e32 v93, v93, v94
	v_cndmask_b32_e64 v94, v99, v95, s[4:5]
	v_cndmask_b32_e64 v95, v95, v99, s[4:5]
	v_mov_b32_e32 v97, v95
	s_nop 1
	v_permlane16_swap_b32_e32 v95, v97
	v_add_f32_e32 v100, v102, v100
	v_cndmask_b32_e64 v95, v95, v97, s[14:15]
	v_add_f32_e32 v94, v94, v95
	v_cndmask_b32_e64 v95, v100, v96, s[4:5]
	v_cndmask_b32_e64 v96, v96, v100, s[4:5]
	v_mov_b32_e32 v97, v96
	s_nop 1
	v_permlane16_swap_b32_e32 v96, v97
	v_cndmask_b32_e64 v96, v96, v97, s[14:15]
	v_add_f32_e32 v92, v101, v92
	v_add_f32_e32 v95, v95, v96
	v_cndmask_b32_e64 v96, v94, v92, s[6:7]
	v_cndmask_b32_e64 v92, v92, v94, s[6:7]
	v_cndmask_b32_e64 v94, v95, v93, s[6:7]
	v_cndmask_b32_e64 v93, v93, v95, s[6:7]
	v_add_f32_dpp v92, v92, v96 row_ror:8 row_mask:0xf bank_mask:0xf bound_ctrl:1
	v_lshl_add_u64 v[52:53], v[46:47], 0, s[84:85]
	v_add_f32_dpp v93, v93, v94 row_ror:8 row_mask:0xf bank_mask:0xf bound_ctrl:1
	v_cndmask_b32_e64 v94, v93, v92, s[8:9]
	v_cndmask_b32_e64 v92, v92, v93, s[8:9]
	s_nop 1
	v_mov_b32_dpp v92, v92 row_half_mirror row_mask:0xf bank_mask:0xf bound_ctrl:1
	s_nop 1
	v_add_f32_dpp v92, v92, v94 quad_perm:[3,2,1,0] row_mask:0xf bank_mask:0xf bound_ctrl:1
	s_nop 1
	v_add_f32_dpp v92, v92, v92 quad_perm:[2,3,0,1] row_mask:0xf bank_mask:0xf bound_ctrl:1
	s_nop 1
	v_mov_b32_dpp v93, v92 quad_perm:[1,0,3,2] row_mask:0xf bank_mask:0xf bound_ctrl:1
	s_and_saveexec_b64 s[42:43], s[10:11]
	s_cbranch_execz .LBB0_895
	v_lshl_add_u64 v[94:95], s[40:41], 0, v[2:3]
	global_load_ushort v2, v[94:95], off
	v_add_f32_e32 v94, v92, v93
	s_lshl_b64 s[40:41], s[34:35], 10
	v_lshl_add_u64 v[92:93], v[52:53], 0, s[40:41]
	v_add_co_u32_e32 v92, vcc, 0x1000000, v92
	s_movk_i32 s36, 0x7fff
	s_nop 0
	v_addc_co_u32_e32 v93, vcc, 0, v93, vcc
	s_waitcnt vmcnt(0)
	v_lshlrev_b32_e32 v2, 16, v2
	v_fmac_f32_e32 v94, v58, v2
	v_mul_f32_e32 v2, 0x3d372713, v94
	v_mul_f32_e32 v2, v94, v2
	v_fma_f32 v2, v94, v2, v94
	v_mul_f32_e32 v2, 0x3fcc422a, v2
	v_mul_f32_e32 v2, 0xbfb8aa3b, v2
	v_exp_f32_e32 v2, v2
	s_nop 0
	v_add_f32_e32 v2, 1.0, v2
	v_rcp_f32_e32 v2, v2
	s_nop 0
	v_mul_f32_e32 v2, v94, v2
	v_bfe_u32 v94, v2, 16, 1
	v_add3_u32 v2, v2, v94, s36
	global_store_short_d16_hi v[92:93], v2, off
